# in-proj hyena-column tiles: transposed store staged through per-wave LDS (16-byte stores instead of 128 two-byte stores per lane), on top of reduced-MFMA hyena conv and 1/7 split
# speedup vs baseline: 1.0458x; 1.0037x over previous
.LBB0_330:
	ds_read_b128 v[146:149], v152
	ds_read_b128 v[156:159], v152 offset:1024
	ds_read_b128 v[160:163], v152 offset:2048
	ds_read_b128 v[164:167], v152 offset:3072
	s_add_u32 s54, s36, 0xfff80080
	s_addc_u32 s55, s37, -1
	s_cmp_eq_u32 s78, 28
	s_cselect_b32 s57, s1, s55
	s_cselect_b32 s56, s15, s54
	s_cselect_b32 s55, s13, s35
	s_cselect_b32 s54, s28, s29
	v_lshl_add_u64 v[200:201], s[36:37], 0, v[138:139]
	s_add_i32 m0, s61, 0xc000
	ds_read_b128 v[168:171], v153
	ds_read_b128 v[172:175], v153 offset:1024
	ds_read_b128 v[176:179], v153 offset:2048
	ds_read_b128 v[180:183], v153 offset:3072
	ds_read_b128 v[184:187], v153 offset:4096
	ds_read_b128 v[188:191], v153 offset:5120
	ds_read_b128 v[192:195], v153 offset:6144
	ds_read_b128 v[196:199], v153 offset:7168
	global_load_lds_dwordx4 v[200:201], off
	v_lshl_add_u64 v[200:201], s[36:37], 0, v[140:141]
	s_add_i32 m0, s61, 0xe000
	s_nop 0
	global_load_lds_dwordx4 v[200:201], off
	s_waitcnt lgkmcnt(8)
	s_barrier
	s_waitcnt lgkmcnt(0)
	s_setprio 1
	s_waitcnt lgkmcnt(0)
	v_mfma_f32_16x16x32_bf16 v[124:127], v[146:149], v[168:171], v[124:127]
	v_mfma_f32_16x16x32_bf16 v[120:123], v[160:163], v[168:171], v[120:123]
	v_mfma_f32_16x16x32_bf16 v[108:111], v[146:149], v[176:179], v[108:111]
	v_mfma_f32_16x16x32_bf16 v[104:107], v[160:163], v[176:179], v[104:107]
	v_mfma_f32_16x16x32_bf16 v[92:95], v[146:149], v[184:187], v[92:95]
	v_mfma_f32_16x16x32_bf16 v[88:91], v[160:163], v[184:187], v[88:91]
	v_mfma_f32_16x16x32_bf16 v[76:79], v[146:149], v[192:195], v[76:79]
	v_mfma_f32_16x16x32_bf16 v[72:75], v[160:163], v[192:195], v[72:75]
	v_mfma_f32_16x16x32_bf16 v[124:127], v[156:159], v[172:175], v[124:127]
	v_mfma_f32_16x16x32_bf16 v[120:123], v[164:167], v[172:175], v[120:123]
	v_mfma_f32_16x16x32_bf16 v[108:111], v[156:159], v[180:183], v[108:111]
	v_mfma_f32_16x16x32_bf16 v[104:107], v[164:167], v[180:183], v[104:107]
	v_mfma_f32_16x16x32_bf16 v[92:95], v[156:159], v[188:191], v[92:95]
	v_mfma_f32_16x16x32_bf16 v[88:91], v[164:167], v[188:191], v[88:91]
	v_mfma_f32_16x16x32_bf16 v[76:79], v[156:159], v[196:199], v[76:79]
	v_mfma_f32_16x16x32_bf16 v[72:75], v[164:167], v[196:199], v[72:75]
	s_setprio 0
	s_barrier
	s_add_i32 s79, s75, s60
	v_lshl_add_u64 v[216:217], s[54:55], 0, v[130:131]
	s_mov_b32 m0, s79
	ds_read_b128 v[200:203], v154
	ds_read_b128 v[204:207], v154 offset:1024
	ds_read_b128 v[208:211], v154 offset:2048
	ds_read_b128 v[212:215], v154 offset:3072
	global_load_lds_dwordx4 v[216:217], off
	v_lshl_add_u64 v[218:219], s[54:55], 0, v[134:135]
	s_add_i32 m0, s79, 0x2000
	s_nop 0
	global_load_lds_dwordx4 v[218:219], off
	s_barrier
	s_waitcnt lgkmcnt(0)
	s_setprio 1
	s_waitcnt lgkmcnt(0)
	v_mfma_f32_16x16x32_bf16 v[116:119], v[200:203], v[168:171], v[116:119]
	v_mfma_f32_16x16x32_bf16 v[112:115], v[208:211], v[168:171], v[112:115]
	v_mfma_f32_16x16x32_bf16 v[100:103], v[200:203], v[176:179], v[100:103]
	v_mfma_f32_16x16x32_bf16 v[96:99], v[208:211], v[176:179], v[96:99]
	v_mfma_f32_16x16x32_bf16 v[84:87], v[200:203], v[184:187], v[84:87]
	v_mfma_f32_16x16x32_bf16 v[80:83], v[208:211], v[184:187], v[80:83]
	v_mfma_f32_16x16x32_bf16 v[68:71], v[200:203], v[192:195], v[68:71]
	v_mfma_f32_16x16x32_bf16 v[64:67], v[208:211], v[192:195], v[64:67]
	v_mfma_f32_16x16x32_bf16 v[116:119], v[204:207], v[172:175], v[116:119]
	v_mfma_f32_16x16x32_bf16 v[112:115], v[212:215], v[172:175], v[112:115]
	v_mfma_f32_16x16x32_bf16 v[100:103], v[204:207], v[180:183], v[100:103]
	v_mfma_f32_16x16x32_bf16 v[96:99], v[212:215], v[180:183], v[96:99]
	v_mfma_f32_16x16x32_bf16 v[84:87], v[204:207], v[188:191], v[84:87]
	v_mfma_f32_16x16x32_bf16 v[80:83], v[212:215], v[188:191], v[80:83]
	v_mfma_f32_16x16x32_bf16 v[68:71], v[204:207], v[196:199], v[68:71]
	v_mfma_f32_16x16x32_bf16 v[64:67], v[212:215], v[196:199], v[64:67]
	s_setprio 0
	s_mov_b32 m0, s61
	v_lshl_add_u64 v[220:221], s[56:57], 0, v[128:129]
	s_barrier
	ds_read_b128 v[168:171], v153 offset:16384
	ds_read_b128 v[172:175], v153 offset:17408
	ds_read_b128 v[176:179], v153 offset:18432
	ds_read_b128 v[180:183], v153 offset:19456
	ds_read_b128 v[184:187], v153 offset:20480
	ds_read_b128 v[188:191], v153 offset:21504
	ds_read_b128 v[192:195], v153 offset:22528
	ds_read_b128 v[196:199], v153 offset:23552
	global_load_lds_dwordx4 v[220:221], off
	v_lshl_add_u64 v[222:223], s[56:57], 0, v[132:133]
	s_mov_b32 m0, s62
	s_nop 0
	global_load_lds_dwordx4 v[222:223], off
	s_barrier
	s_waitcnt lgkmcnt(0)
	s_setprio 1
	s_waitcnt lgkmcnt(0)
	v_mfma_f32_16x16x32_bf16 v[60:63], v[146:149], v[168:171], v[60:63]
	v_mfma_f32_16x16x32_bf16 v[56:59], v[160:163], v[168:171], v[56:59]
	v_mfma_f32_16x16x32_bf16 v[44:47], v[146:149], v[176:179], v[44:47]
	v_mfma_f32_16x16x32_bf16 v[40:43], v[160:163], v[176:179], v[40:43]
	v_mfma_f32_16x16x32_bf16 v[28:31], v[146:149], v[184:187], v[28:31]
	v_mfma_f32_16x16x32_bf16 v[24:27], v[160:163], v[184:187], v[24:27]
	v_mfma_f32_16x16x32_bf16 v[12:15], v[146:149], v[192:195], v[12:15]
	v_mfma_f32_16x16x32_bf16 v[8:11], v[160:163], v[192:195], v[8:11]
	v_mfma_f32_16x16x32_bf16 v[60:63], v[156:159], v[172:175], v[60:63]
	v_mfma_f32_16x16x32_bf16 v[56:59], v[164:167], v[172:175], v[56:59]
	v_mfma_f32_16x16x32_bf16 v[44:47], v[156:159], v[180:183], v[44:47]
	v_mfma_f32_16x16x32_bf16 v[40:43], v[164:167], v[180:183], v[40:43]
	v_mfma_f32_16x16x32_bf16 v[28:31], v[156:159], v[188:191], v[28:31]
	v_mfma_f32_16x16x32_bf16 v[24:27], v[164:167], v[188:191], v[24:27]
	v_mfma_f32_16x16x32_bf16 v[12:15], v[156:159], v[196:199], v[12:15]
	v_mfma_f32_16x16x32_bf16 v[8:11], v[164:167], v[196:199], v[8:11]
	s_setprio 0
	s_barrier
	s_add_u32 s80, s54, 0x80000
	s_addc_u32 s81, s55, 0
	s_add_i32 s79, s76, s60
	v_lshl_add_u64 v[146:147], s[80:81], 0, v[130:131]
	s_mov_b32 m0, s79
	s_nop 0
	global_load_lds_dwordx4 v[146:147], off
	v_lshl_add_u64 v[146:147], s[80:81], 0, v[134:135]
	s_add_i32 m0, s79, 0x2000
	s_nop 0
	global_load_lds_dwordx4 v[146:147], off
	s_waitcnt vmcnt(6)
	s_barrier
	s_setprio 1
	v_mfma_f32_16x16x32_bf16 v[52:55], v[200:203], v[168:171], v[52:55]
	v_mfma_f32_16x16x32_bf16 v[48:51], v[208:211], v[168:171], v[48:51]
	v_mfma_f32_16x16x32_bf16 v[36:39], v[200:203], v[176:179], v[36:39]
	v_mfma_f32_16x16x32_bf16 v[32:35], v[208:211], v[176:179], v[32:35]
	v_mfma_f32_16x16x32_bf16 v[20:23], v[200:203], v[184:187], v[20:23]
	v_mfma_f32_16x16x32_bf16 v[16:19], v[208:211], v[184:187], v[16:19]
	v_mfma_f32_16x16x32_bf16 v[4:7], v[200:203], v[192:195], v[4:7]
	v_mfma_f32_16x16x32_bf16 v[0:3], v[208:211], v[192:195], v[0:3]
	v_mfma_f32_16x16x32_bf16 v[52:55], v[204:207], v[172:175], v[52:55]
	v_mfma_f32_16x16x32_bf16 v[48:51], v[212:215], v[172:175], v[48:51]
	v_mfma_f32_16x16x32_bf16 v[36:39], v[204:207], v[180:183], v[36:39]
	v_mfma_f32_16x16x32_bf16 v[32:35], v[212:215], v[180:183], v[32:35]
	v_mfma_f32_16x16x32_bf16 v[20:23], v[204:207], v[188:191], v[20:23]
	v_mfma_f32_16x16x32_bf16 v[16:19], v[212:215], v[188:191], v[16:19]
	v_mfma_f32_16x16x32_bf16 v[4:7], v[204:207], v[196:199], v[4:7]
	v_mfma_f32_16x16x32_bf16 v[0:3], v[212:215], v[196:199], v[0:3]
	s_setprio 0
	s_add_i32 s79, 0, 0x18000
	v_add_u32_e32 v155, s79, v150
	s_barrier
	ds_read_b128 v[146:149], v155
	ds_read_b128 v[156:159], v155 offset:1024
	ds_read_b128 v[160:163], v155 offset:2048
	ds_read_b128 v[164:167], v155 offset:3072
	s_add_u32 s56, s56, 0x80000
	s_addc_u32 s57, s57, 0
	s_mov_b32 m0, s63
	v_lshl_add_u64 v[200:201], s[56:57], 0, v[128:129]
	ds_read_b128 v[168:171], v153 offset:32768
	ds_read_b128 v[172:175], v153 offset:33792
	ds_read_b128 v[176:179], v153 offset:34816
	ds_read_b128 v[180:183], v153 offset:35840
	ds_read_b128 v[184:187], v153 offset:36864
	ds_read_b128 v[188:191], v153 offset:37888
	ds_read_b128 v[192:195], v153 offset:38912
	ds_read_b128 v[196:199], v153 offset:39936
	global_load_lds_dwordx4 v[200:201], off
	v_lshl_add_u64 v[200:201], s[56:57], 0, v[132:133]
	s_mov_b32 m0, s64
	s_nop 0
	global_load_lds_dwordx4 v[200:201], off
	s_waitcnt lgkmcnt(8)
	s_barrier
	s_waitcnt lgkmcnt(0)
	s_setprio 1
	s_waitcnt lgkmcnt(0)
	v_mfma_f32_16x16x32_bf16 v[124:127], v[146:149], v[168:171], v[124:127]
	v_mfma_f32_16x16x32_bf16 v[120:123], v[160:163], v[168:171], v[120:123]
	v_mfma_f32_16x16x32_bf16 v[108:111], v[146:149], v[176:179], v[108:111]
	v_mfma_f32_16x16x32_bf16 v[104:107], v[160:163], v[176:179], v[104:107]
	v_mfma_f32_16x16x32_bf16 v[92:95], v[146:149], v[184:187], v[92:95]
	v_mfma_f32_16x16x32_bf16 v[88:91], v[160:163], v[184:187], v[88:91]
	v_mfma_f32_16x16x32_bf16 v[76:79], v[146:149], v[192:195], v[76:79]
	v_mfma_f32_16x16x32_bf16 v[72:75], v[160:163], v[192:195], v[72:75]
	v_mfma_f32_16x16x32_bf16 v[124:127], v[156:159], v[172:175], v[124:127]
	v_mfma_f32_16x16x32_bf16 v[120:123], v[164:167], v[172:175], v[120:123]
	v_mfma_f32_16x16x32_bf16 v[108:111], v[156:159], v[180:183], v[108:111]
	v_mfma_f32_16x16x32_bf16 v[104:107], v[164:167], v[180:183], v[104:107]
	v_mfma_f32_16x16x32_bf16 v[92:95], v[156:159], v[188:191], v[92:95]
	v_mfma_f32_16x16x32_bf16 v[88:91], v[164:167], v[188:191], v[88:91]
	v_mfma_f32_16x16x32_bf16 v[76:79], v[156:159], v[196:199], v[76:79]
	v_mfma_f32_16x16x32_bf16 v[72:75], v[164:167], v[196:199], v[72:75]
	s_setprio 0
	s_barrier
	s_add_i32 s56, 0, 0x1c000
	s_add_i32 s57, s79, s60
	v_add_u32_e32 v155, s56, v150
	v_lshl_add_u64 v[216:217], v[216:217], 0, s[10:11]
	s_mov_b32 m0, s57
	ds_read_b128 v[200:203], v155
	ds_read_b128 v[204:207], v155 offset:1024
	ds_read_b128 v[208:211], v155 offset:2048
	ds_read_b128 v[212:215], v155 offset:3072
	global_load_lds_dwordx4 v[216:217], off
	v_lshl_add_u64 v[216:217], v[218:219], 0, s[10:11]
	s_add_i32 m0, s57, 0x2000
	s_nop 0
	global_load_lds_dwordx4 v[216:217], off
	s_barrier
	s_waitcnt lgkmcnt(0)
	s_setprio 1
	s_waitcnt lgkmcnt(0)
	v_mfma_f32_16x16x32_bf16 v[116:119], v[200:203], v[168:171], v[116:119]
	v_mfma_f32_16x16x32_bf16 v[112:115], v[208:211], v[168:171], v[112:115]
	v_mfma_f32_16x16x32_bf16 v[100:103], v[200:203], v[176:179], v[100:103]
	v_mfma_f32_16x16x32_bf16 v[96:99], v[208:211], v[176:179], v[96:99]
	v_mfma_f32_16x16x32_bf16 v[84:87], v[200:203], v[184:187], v[84:87]
	v_mfma_f32_16x16x32_bf16 v[80:83], v[208:211], v[184:187], v[80:83]
	v_mfma_f32_16x16x32_bf16 v[68:71], v[200:203], v[192:195], v[68:71]
	v_mfma_f32_16x16x32_bf16 v[64:67], v[208:211], v[192:195], v[64:67]
	v_mfma_f32_16x16x32_bf16 v[116:119], v[204:207], v[172:175], v[116:119]
	v_mfma_f32_16x16x32_bf16 v[112:115], v[212:215], v[172:175], v[112:115]
	v_mfma_f32_16x16x32_bf16 v[100:103], v[204:207], v[180:183], v[100:103]
	v_mfma_f32_16x16x32_bf16 v[96:99], v[212:215], v[180:183], v[96:99]
	v_mfma_f32_16x16x32_bf16 v[84:87], v[204:207], v[188:191], v[84:87]
	v_mfma_f32_16x16x32_bf16 v[80:83], v[212:215], v[188:191], v[80:83]
	v_mfma_f32_16x16x32_bf16 v[68:71], v[204:207], v[196:199], v[68:71]
	v_mfma_f32_16x16x32_bf16 v[64:67], v[212:215], v[196:199], v[64:67]
	s_setprio 0
	s_mov_b32 m0, s66
	v_lshl_add_u64 v[216:217], v[220:221], 0, s[10:11]
	s_barrier
	ds_read_b128 v[168:171], v153 offset:49152
	ds_read_b128 v[172:175], v153 offset:50176
	ds_read_b128 v[176:179], v153 offset:51200
	ds_read_b128 v[180:183], v153 offset:52224
	ds_read_b128 v[184:187], v153 offset:53248
	ds_read_b128 v[188:191], v153 offset:54272
	ds_read_b128 v[192:195], v153 offset:55296
	ds_read_b128 v[196:199], v153 offset:56320
	global_load_lds_dwordx4 v[216:217], off
	v_lshl_add_u64 v[216:217], v[222:223], 0, s[10:11]
	s_mov_b32 m0, s67
	s_nop 0
	global_load_lds_dwordx4 v[216:217], off
	s_barrier
	s_waitcnt lgkmcnt(0)
	s_setprio 1
	s_waitcnt lgkmcnt(0)
	v_mfma_f32_16x16x32_bf16 v[60:63], v[146:149], v[168:171], v[60:63]
	v_mfma_f32_16x16x32_bf16 v[56:59], v[160:163], v[168:171], v[56:59]
	v_mfma_f32_16x16x32_bf16 v[44:47], v[146:149], v[176:179], v[44:47]
	v_mfma_f32_16x16x32_bf16 v[40:43], v[160:163], v[176:179], v[40:43]
	v_mfma_f32_16x16x32_bf16 v[28:31], v[146:149], v[184:187], v[28:31]
	v_mfma_f32_16x16x32_bf16 v[24:27], v[160:163], v[184:187], v[24:27]
	v_mfma_f32_16x16x32_bf16 v[12:15], v[146:149], v[192:195], v[12:15]
	v_mfma_f32_16x16x32_bf16 v[8:11], v[160:163], v[192:195], v[8:11]
	v_mfma_f32_16x16x32_bf16 v[60:63], v[156:159], v[172:175], v[60:63]
	v_mfma_f32_16x16x32_bf16 v[56:59], v[164:167], v[172:175], v[56:59]
	v_mfma_f32_16x16x32_bf16 v[44:47], v[156:159], v[180:183], v[44:47]
	v_mfma_f32_16x16x32_bf16 v[40:43], v[164:167], v[180:183], v[40:43]
	v_mfma_f32_16x16x32_bf16 v[28:31], v[156:159], v[188:191], v[28:31]
	v_mfma_f32_16x16x32_bf16 v[24:27], v[164:167], v[188:191], v[24:27]
	v_mfma_f32_16x16x32_bf16 v[12:15], v[156:159], v[196:199], v[12:15]
	v_mfma_f32_16x16x32_bf16 v[8:11], v[164:167], v[196:199], v[8:11]
	s_setprio 0
	s_barrier
	s_add_u32 s54, s54, 0x80080
	s_addc_u32 s55, s55, 0
	s_add_i32 s56, s56, s60
	v_lshl_add_u64 v[146:147], s[54:55], 0, v[130:131]
	s_mov_b32 m0, s56
	s_nop 0
	global_load_lds_dwordx4 v[146:147], off
	v_lshl_add_u64 v[146:147], s[54:55], 0, v[134:135]
	s_add_i32 m0, s56, 0x2000
	s_nop 0
	global_load_lds_dwordx4 v[146:147], off
	s_waitcnt vmcnt(6)
	s_barrier
	s_setprio 1
	v_mfma_f32_16x16x32_bf16 v[52:55], v[200:203], v[168:171], v[52:55]
	v_mfma_f32_16x16x32_bf16 v[48:51], v[208:211], v[168:171], v[48:51]
	v_mfma_f32_16x16x32_bf16 v[36:39], v[200:203], v[176:179], v[36:39]
	v_mfma_f32_16x16x32_bf16 v[32:35], v[208:211], v[176:179], v[32:35]
	v_mfma_f32_16x16x32_bf16 v[20:23], v[200:203], v[184:187], v[20:23]
	v_mfma_f32_16x16x32_bf16 v[16:19], v[208:211], v[184:187], v[16:19]
	v_mfma_f32_16x16x32_bf16 v[4:7], v[200:203], v[192:195], v[4:7]
	v_mfma_f32_16x16x32_bf16 v[0:3], v[208:211], v[192:195], v[0:3]
	v_mfma_f32_16x16x32_bf16 v[52:55], v[204:207], v[172:175], v[52:55]
	v_mfma_f32_16x16x32_bf16 v[48:51], v[212:215], v[172:175], v[48:51]
	v_mfma_f32_16x16x32_bf16 v[36:39], v[204:207], v[180:183], v[36:39]
	v_mfma_f32_16x16x32_bf16 v[32:35], v[212:215], v[180:183], v[32:35]
	v_mfma_f32_16x16x32_bf16 v[20:23], v[204:207], v[188:191], v[20:23]
	v_mfma_f32_16x16x32_bf16 v[16:19], v[212:215], v[188:191], v[16:19]
	v_mfma_f32_16x16x32_bf16 v[4:7], v[204:207], v[196:199], v[4:7]
	v_mfma_f32_16x16x32_bf16 v[0:3], v[212:215], v[196:199], v[0:3]
	s_setprio 0
	s_add_i32 s78, s78, 2
	s_add_u32 s36, s36, 0x100
	s_addc_u32 s37, s37, 0
	s_add_u32 s29, s29, 0x100
	s_addc_u32 s35, s35, 0
	s_cmp_gt_u32 s78, 29
	s_barrier
	s_cbranch_scc0 .LBB0_330
	s_cmp_gt_i32 s34, 3
	v_lshl_add_u32 v146, s0, 8, v145
	v_lshl_or_b32 v148, s34, 8, v151
	s_cselect_b64 s[34:35], -1, 0
	v_ashrrev_i32_e32 v147, 31, v146
	s_mov_b64 s[0:1], -1
	s_and_b64 vcc, exec, s[34:35]
	v_ashrrev_i32_e32 v149, 31, v148
	s_cbranch_vccz .LBB0_333
	v_and_b32_e32 v160, 63, v144
	v_lshrrev_b32_e32 v161, 6, v144
	v_lshlrev_b32_e32 v162, 10, v161
	v_add_u32_e32 v162, 0x20000, v162
	v_lshrrev_b32_e32 v163, 4, v160
	v_and_b32_e32 v164, 15, v160
	v_lshlrev_b32_e32 v165, 8, v163
	v_lshl_add_u32 v165, v164, 1, v165
	v_add_u32_e32 v165, v162, v165
	v_lshl_add_u32 v166, v160, 4, v162
	v_sub_u32_e32 v167, v148, v151
	v_and_b32_e32 v168, 0x60, v151
	v_add_u32_e32 v167, v167, v168
	v_lshl_add_u32 v167, v163, 3, v167
	v_bfe_u32 v168, v160, 2, 2
	v_add_u32_e32 v167, v167, v168
	v_sub_u32_e32 v168, v146, v145
	v_and_b32_e32 v169, 0x40, v145
	v_add_u32_e32 v168, v168, v169
	v_and_b32_e32 v169, 3, v160
	v_lshl_add_u32 v168, v169, 3, v168
	v_mov_b32_e32 v170, v167
	v_mov_b32_e32 v171, 0
	v_lshlrev_b64 v[170:171], 15, v[170:171]
	v_lshl_add_u64 v[170:171], s[8:9], 0, v[170:171]
	v_lshlrev_b32_e32 v172, 1, v168
	v_mov_b32_e32 v173, 0
	v_lshl_add_u64 v[170:171], v[170:171], 0, v[172:173]
	s_mov_b32 s28, 0xfe000000
	s_mov_b32 s29, -1
	v_lshl_add_u64 v[170:171], v[170:171], 0, s[28:29]
	s_mov_b32 s29, 0
	v_cvt_pk_bf16_f32 v190, v124, v125
	v_cvt_pk_bf16_f32 v191, v126, v127
	v_lshrrev_b32_e32 v192, 16, v190
	v_lshrrev_b32_e32 v193, 16, v191
	ds_write_b16 v165, v190 offset:0
	ds_write_b16 v165, v192 offset:64
	ds_write_b16 v165, v191 offset:128
	ds_write_b16 v165, v193 offset:192
	v_cvt_pk_bf16_f32 v198, v108, v109
	v_cvt_pk_bf16_f32 v199, v110, v111
	v_lshrrev_b32_e32 v200, 16, v198
	v_lshrrev_b32_e32 v201, 16, v199
	ds_write_b16 v165, v198 offset:32
	ds_write_b16 v165, v200 offset:96
	ds_write_b16 v165, v199 offset:160
	ds_write_b16 v165, v201 offset:224
	ds_read_b128 v[180:183], v166
	s_waitcnt lgkmcnt(0)
	global_store_dwordx4 v[170:171], v[180:183], off
	v_cvt_pk_bf16_f32 v194, v92, v93
	v_cvt_pk_bf16_f32 v195, v94, v95
	v_lshrrev_b32_e32 v196, 16, v194
	v_lshrrev_b32_e32 v197, 16, v195
	ds_write_b16 v165, v194 offset:0
	ds_write_b16 v165, v196 offset:64
	ds_write_b16 v165, v195 offset:128
	ds_write_b16 v165, v197 offset:192
	v_cvt_pk_bf16_f32 v202, v76, v77
	v_cvt_pk_bf16_f32 v203, v78, v79
	v_lshrrev_b32_e32 v204, 16, v202
	v_lshrrev_b32_e32 v205, 16, v203
	ds_write_b16 v165, v202 offset:32
	ds_write_b16 v165, v204 offset:96
	ds_write_b16 v165, v203 offset:160
	ds_write_b16 v165, v205 offset:224
	ds_read_b128 v[184:187], v166
	s_waitcnt lgkmcnt(0)
	global_store_dwordx4 v[170:171], v[184:187], off offset:64
	v_cvt_pk_bf16_f32 v190, v60, v61
	v_cvt_pk_bf16_f32 v191, v62, v63
	v_lshrrev_b32_e32 v192, 16, v190
	v_lshrrev_b32_e32 v193, 16, v191
	ds_write_b16 v165, v190 offset:0
	ds_write_b16 v165, v192 offset:64
	ds_write_b16 v165, v191 offset:128
	ds_write_b16 v165, v193 offset:192
	v_cvt_pk_bf16_f32 v198, v44, v45
	v_cvt_pk_bf16_f32 v199, v46, v47
	v_lshrrev_b32_e32 v200, 16, v198
	v_lshrrev_b32_e32 v201, 16, v199
	ds_write_b16 v165, v198 offset:32
	ds_write_b16 v165, v200 offset:96
	ds_write_b16 v165, v199 offset:160
	ds_write_b16 v165, v201 offset:224
	ds_read_b128 v[180:183], v166
	s_waitcnt lgkmcnt(0)
	global_store_dwordx4 v[170:171], v[180:183], off offset:256
	v_cvt_pk_bf16_f32 v194, v28, v29
	v_cvt_pk_bf16_f32 v195, v30, v31
	v_lshrrev_b32_e32 v196, 16, v194
	v_lshrrev_b32_e32 v197, 16, v195
	ds_write_b16 v165, v194 offset:0
	ds_write_b16 v165, v196 offset:64
	ds_write_b16 v165, v195 offset:128
	ds_write_b16 v165, v197 offset:192
	v_cvt_pk_bf16_f32 v202, v12, v13
	v_cvt_pk_bf16_f32 v203, v14, v15
	v_lshrrev_b32_e32 v204, 16, v202
	v_lshrrev_b32_e32 v205, 16, v203
	ds_write_b16 v165, v202 offset:32
	ds_write_b16 v165, v204 offset:96
	ds_write_b16 v165, v203 offset:160
	ds_write_b16 v165, v205 offset:224
	ds_read_b128 v[184:187], v166
	s_waitcnt lgkmcnt(0)
	global_store_dwordx4 v[170:171], v[184:187], off offset:320
	s_mov_b32 s28, 0x20000
	v_lshl_add_u64 v[174:175], v[170:171], 0, s[28:29]
	v_cvt_pk_bf16_f32 v190, v120, v121
	v_cvt_pk_bf16_f32 v191, v122, v123
	v_lshrrev_b32_e32 v192, 16, v190
	v_lshrrev_b32_e32 v193, 16, v191
	ds_write_b16 v165, v190 offset:0
	ds_write_b16 v165, v192 offset:64
	ds_write_b16 v165, v191 offset:128
	ds_write_b16 v165, v193 offset:192
	v_cvt_pk_bf16_f32 v198, v104, v105
	v_cvt_pk_bf16_f32 v199, v106, v107
	v_lshrrev_b32_e32 v200, 16, v198
	v_lshrrev_b32_e32 v201, 16, v199
	ds_write_b16 v165, v198 offset:32
	ds_write_b16 v165, v200 offset:96
	ds_write_b16 v165, v199 offset:160
	ds_write_b16 v165, v201 offset:224
	ds_read_b128 v[180:183], v166
	s_waitcnt lgkmcnt(0)
	global_store_dwordx4 v[174:175], v[180:183], off
	v_cvt_pk_bf16_f32 v194, v88, v89
	v_cvt_pk_bf16_f32 v195, v90, v91
	v_lshrrev_b32_e32 v196, 16, v194
	v_lshrrev_b32_e32 v197, 16, v195
	ds_write_b16 v165, v194 offset:0
	ds_write_b16 v165, v196 offset:64
	ds_write_b16 v165, v195 offset:128
	ds_write_b16 v165, v197 offset:192
	v_cvt_pk_bf16_f32 v202, v72, v73
	v_cvt_pk_bf16_f32 v203, v74, v75
	v_lshrrev_b32_e32 v204, 16, v202
	v_lshrrev_b32_e32 v205, 16, v203
	ds_write_b16 v165, v202 offset:32
	ds_write_b16 v165, v204 offset:96
	ds_write_b16 v165, v203 offset:160
	ds_write_b16 v165, v205 offset:224
	ds_read_b128 v[184:187], v166
	s_waitcnt lgkmcnt(0)
	global_store_dwordx4 v[174:175], v[184:187], off offset:64
	v_cvt_pk_bf16_f32 v190, v56, v57
	v_cvt_pk_bf16_f32 v191, v58, v59
	v_lshrrev_b32_e32 v192, 16, v190
	v_lshrrev_b32_e32 v193, 16, v191
	ds_write_b16 v165, v190 offset:0
	ds_write_b16 v165, v192 offset:64
	ds_write_b16 v165, v191 offset:128
	ds_write_b16 v165, v193 offset:192
	v_cvt_pk_bf16_f32 v198, v40, v41
	v_cvt_pk_bf16_f32 v199, v42, v43
	v_lshrrev_b32_e32 v200, 16, v198
	v_lshrrev_b32_e32 v201, 16, v199
	ds_write_b16 v165, v198 offset:32
	ds_write_b16 v165, v200 offset:96
	ds_write_b16 v165, v199 offset:160
	ds_write_b16 v165, v201 offset:224
	ds_read_b128 v[180:183], v166
	s_waitcnt lgkmcnt(0)
	global_store_dwordx4 v[174:175], v[180:183], off offset:256
	v_cvt_pk_bf16_f32 v194, v24, v25
	v_cvt_pk_bf16_f32 v195, v26, v27
	v_lshrrev_b32_e32 v196, 16, v194
	v_lshrrev_b32_e32 v197, 16, v195
	ds_write_b16 v165, v194 offset:0
	ds_write_b16 v165, v196 offset:64
	ds_write_b16 v165, v195 offset:128
	ds_write_b16 v165, v197 offset:192
	v_cvt_pk_bf16_f32 v202, v8, v9
	v_cvt_pk_bf16_f32 v203, v10, v11
	v_lshrrev_b32_e32 v204, 16, v202
	v_lshrrev_b32_e32 v205, 16, v203
	ds_write_b16 v165, v202 offset:32
	ds_write_b16 v165, v204 offset:96
	ds_write_b16 v165, v203 offset:160
	ds_write_b16 v165, v205 offset:224
	ds_read_b128 v[184:187], v166
	s_waitcnt lgkmcnt(0)
	global_store_dwordx4 v[174:175], v[184:187], off offset:320
	s_mov_b32 s28, 0x400000
	v_lshl_add_u64 v[174:175], v[170:171], 0, s[28:29]
	v_cvt_pk_bf16_f32 v190, v116, v117
	v_cvt_pk_bf16_f32 v191, v118, v119
	v_lshrrev_b32_e32 v192, 16, v190
	v_lshrrev_b32_e32 v193, 16, v191
	ds_write_b16 v165, v190 offset:0
	ds_write_b16 v165, v192 offset:64
	ds_write_b16 v165, v191 offset:128
	ds_write_b16 v165, v193 offset:192
	v_cvt_pk_bf16_f32 v198, v100, v101
	v_cvt_pk_bf16_f32 v199, v102, v103
	v_lshrrev_b32_e32 v200, 16, v198
	v_lshrrev_b32_e32 v201, 16, v199
	ds_write_b16 v165, v198 offset:32
	ds_write_b16 v165, v200 offset:96
	ds_write_b16 v165, v199 offset:160
	ds_write_b16 v165, v201 offset:224
	ds_read_b128 v[180:183], v166
	s_waitcnt lgkmcnt(0)
	global_store_dwordx4 v[174:175], v[180:183], off
	v_cvt_pk_bf16_f32 v194, v84, v85
	v_cvt_pk_bf16_f32 v195, v86, v87
	v_lshrrev_b32_e32 v196, 16, v194
	v_lshrrev_b32_e32 v197, 16, v195
	ds_write_b16 v165, v194 offset:0
	ds_write_b16 v165, v196 offset:64
	ds_write_b16 v165, v195 offset:128
	ds_write_b16 v165, v197 offset:192
	v_cvt_pk_bf16_f32 v202, v68, v69
	v_cvt_pk_bf16_f32 v203, v70, v71
	v_lshrrev_b32_e32 v204, 16, v202
	v_lshrrev_b32_e32 v205, 16, v203
	ds_write_b16 v165, v202 offset:32
	ds_write_b16 v165, v204 offset:96
	ds_write_b16 v165, v203 offset:160
	ds_write_b16 v165, v205 offset:224
	ds_read_b128 v[184:187], v166
	s_waitcnt lgkmcnt(0)
	global_store_dwordx4 v[174:175], v[184:187], off offset:64
	v_cvt_pk_bf16_f32 v190, v52, v53
	v_cvt_pk_bf16_f32 v191, v54, v55
	v_lshrrev_b32_e32 v192, 16, v190
	v_lshrrev_b32_e32 v193, 16, v191
	ds_write_b16 v165, v190 offset:0
	ds_write_b16 v165, v192 offset:64
	ds_write_b16 v165, v191 offset:128
	ds_write_b16 v165, v193 offset:192
	v_cvt_pk_bf16_f32 v198, v36, v37
	v_cvt_pk_bf16_f32 v199, v38, v39
	v_lshrrev_b32_e32 v200, 16, v198
	v_lshrrev_b32_e32 v201, 16, v199
	ds_write_b16 v165, v198 offset:32
	ds_write_b16 v165, v200 offset:96
	ds_write_b16 v165, v199 offset:160
	ds_write_b16 v165, v201 offset:224
	ds_read_b128 v[180:183], v166
	s_waitcnt lgkmcnt(0)
	global_store_dwordx4 v[174:175], v[180:183], off offset:256
	v_cvt_pk_bf16_f32 v194, v20, v21
	v_cvt_pk_bf16_f32 v195, v22, v23
	v_lshrrev_b32_e32 v196, 16, v194
	v_lshrrev_b32_e32 v197, 16, v195
	ds_write_b16 v165, v194 offset:0
	ds_write_b16 v165, v196 offset:64
	ds_write_b16 v165, v195 offset:128
	ds_write_b16 v165, v197 offset:192
	v_cvt_pk_bf16_f32 v202, v4, v5
	v_cvt_pk_bf16_f32 v203, v6, v7
	v_lshrrev_b32_e32 v204, 16, v202
	v_lshrrev_b32_e32 v205, 16, v203
	ds_write_b16 v165, v202 offset:32
	ds_write_b16 v165, v204 offset:96
	ds_write_b16 v165, v203 offset:160
	ds_write_b16 v165, v205 offset:224
	ds_read_b128 v[184:187], v166
	s_waitcnt lgkmcnt(0)
	global_store_dwordx4 v[174:175], v[184:187], off offset:320
	s_mov_b32 s28, 0x420000
	v_lshl_add_u64 v[174:175], v[170:171], 0, s[28:29]
	v_cvt_pk_bf16_f32 v190, v112, v113
	v_cvt_pk_bf16_f32 v191, v114, v115
	v_lshrrev_b32_e32 v192, 16, v190
	v_lshrrev_b32_e32 v193, 16, v191
	ds_write_b16 v165, v190 offset:0
	ds_write_b16 v165, v192 offset:64
	ds_write_b16 v165, v191 offset:128
	ds_write_b16 v165, v193 offset:192
	v_cvt_pk_bf16_f32 v198, v96, v97
	v_cvt_pk_bf16_f32 v199, v98, v99
	v_lshrrev_b32_e32 v200, 16, v198
	v_lshrrev_b32_e32 v201, 16, v199
	ds_write_b16 v165, v198 offset:32
	ds_write_b16 v165, v200 offset:96
	ds_write_b16 v165, v199 offset:160
	ds_write_b16 v165, v201 offset:224
	ds_read_b128 v[180:183], v166
	s_waitcnt lgkmcnt(0)
	global_store_dwordx4 v[174:175], v[180:183], off
	v_cvt_pk_bf16_f32 v194, v80, v81
	v_cvt_pk_bf16_f32 v195, v82, v83
	v_lshrrev_b32_e32 v196, 16, v194
	v_lshrrev_b32_e32 v197, 16, v195
	ds_write_b16 v165, v194 offset:0
	ds_write_b16 v165, v196 offset:64
	ds_write_b16 v165, v195 offset:128
	ds_write_b16 v165, v197 offset:192
	v_cvt_pk_bf16_f32 v202, v64, v65
	v_cvt_pk_bf16_f32 v203, v66, v67
	v_lshrrev_b32_e32 v204, 16, v202
	v_lshrrev_b32_e32 v205, 16, v203
	ds_write_b16 v165, v202 offset:32
	ds_write_b16 v165, v204 offset:96
	ds_write_b16 v165, v203 offset:160
	ds_write_b16 v165, v205 offset:224
	ds_read_b128 v[184:187], v166
	s_waitcnt lgkmcnt(0)
	global_store_dwordx4 v[174:175], v[184:187], off offset:64
	v_cvt_pk_bf16_f32 v190, v48, v49
	v_cvt_pk_bf16_f32 v191, v50, v51
	v_lshrrev_b32_e32 v192, 16, v190
	v_lshrrev_b32_e32 v193, 16, v191
	ds_write_b16 v165, v190 offset:0
	ds_write_b16 v165, v192 offset:64
	ds_write_b16 v165, v191 offset:128
	ds_write_b16 v165, v193 offset:192
	v_cvt_pk_bf16_f32 v198, v32, v33
	v_cvt_pk_bf16_f32 v199, v34, v35
	v_lshrrev_b32_e32 v200, 16, v198
	v_lshrrev_b32_e32 v201, 16, v199
	ds_write_b16 v165, v198 offset:32
	ds_write_b16 v165, v200 offset:96
	ds_write_b16 v165, v199 offset:160
	ds_write_b16 v165, v201 offset:224
	ds_read_b128 v[180:183], v166
	s_waitcnt lgkmcnt(0)
	global_store_dwordx4 v[174:175], v[180:183], off offset:256
	v_cvt_pk_bf16_f32 v194, v16, v17
	v_cvt_pk_bf16_f32 v195, v18, v19
	v_lshrrev_b32_e32 v196, 16, v194
	v_lshrrev_b32_e32 v197, 16, v195
	ds_write_b16 v165, v194 offset:0
	ds_write_b16 v165, v196 offset:64
	ds_write_b16 v165, v195 offset:128
	ds_write_b16 v165, v197 offset:192
	v_cvt_pk_bf16_f32 v202, v0, v1
	v_cvt_pk_bf16_f32 v203, v2, v3
	v_lshrrev_b32_e32 v204, 16, v202
	v_lshrrev_b32_e32 v205, 16, v203
	ds_write_b16 v165, v202 offset:32
	ds_write_b16 v165, v204 offset:96
	ds_write_b16 v165, v203 offset:160
	ds_write_b16 v165, v205 offset:224
	ds_read_b128 v[184:187], v166
	s_waitcnt lgkmcnt(0)
	global_store_dwordx4 v[174:175], v[184:187], off offset:320
	s_branch .LBB0_319
	v_lshlrev_b64 v[156:157], 15, v[148:149]
	v_lshl_add_u64 v[156:157], s[8:9], 0, v[156:157]
	v_lshl_add_u64 v[156:157], v[146:147], 1, v[156:157]
	v_add_co_u32_e32 v158, vcc, 0xfe000000, v156
	v_cvt_pk_bf16_f32 v155, v124, s0
	s_nop 0
	v_addc_co_u32_e32 v159, vcc, -1, v157, vcc
	global_store_short v[158:159], v155, off
	v_add_co_u32_e32 v158, vcc, 0xfe020000, v156
	v_cvt_pk_bf16_f32 v155, v120, s0
	s_nop 0
	v_addc_co_u32_e32 v159, vcc, -1, v157, vcc
	global_store_short v[158:159], v155, off
	v_add_co_u32_e32 v158, vcc, 0xfe008000, v156
	v_cvt_pk_bf16_f32 v155, v125, s0
	s_nop 0
	v_addc_co_u32_e32 v159, vcc, -1, v157, vcc
	global_store_short v[158:159], v155, off
	v_add_co_u32_e32 v158, vcc, 0xfe028000, v156
	v_cvt_pk_bf16_f32 v155, v121, s0
	s_nop 0
	v_addc_co_u32_e32 v159, vcc, -1, v157, vcc
	global_store_short v[158:159], v155, off
	v_add_co_u32_e32 v158, vcc, 0xfe010000, v156
	v_cvt_pk_bf16_f32 v155, v126, s0
	s_nop 0
	v_addc_co_u32_e32 v159, vcc, -1, v157, vcc
	global_store_short v[158:159], v155, off
	v_add_co_u32_e32 v158, vcc, 0xfe030000, v156
	v_cvt_pk_bf16_f32 v155, v122, s0
	s_nop 0
	v_addc_co_u32_e32 v159, vcc, -1, v157, vcc
	global_store_short v[158:159], v155, off
	v_add_co_u32_e32 v158, vcc, 0xfe018000, v156
	v_cvt_pk_bf16_f32 v155, v127, s0
	s_nop 0
	v_addc_co_u32_e32 v159, vcc, -1, v157, vcc
	v_add_co_u32_e32 v156, vcc, 0xfe038000, v156
	global_store_short v[158:159], v155, off
	v_cvt_pk_bf16_f32 v155, v123, s0
	v_addc_co_u32_e32 v157, vcc, -1, v157, vcc
	global_store_short v[156:157], v155, off
	s_mov_b64 s[0:1], 0
